# batched loads in the final normaliser-state loop (was one load per wait, 128 round trips per tile) + residual copy fast path, on top of v18
# speedup vs baseline: 1.0428x; 1.0316x over previous
.LBB0_63:
	s_or_b64 exec, exec, s[8:9]
	s_mov_b32 s0, s84
	s_nop 0
	v_lshl_add_u32 v2, s0, 8, v42
	s_mov_b32 s0, 0x300000
	v_cmp_gt_i32_e32 vcc, s0, v2
	s_and_saveexec_b64 s[0:1], vcc
	s_cbranch_execz .LBB0_66
	s_load_dword s12, s[86:87], 0xa8
	s_waitcnt lgkmcnt(0)
	s_cmpk_lg_i32 s12, 0x200
	s_cbranch_scc1 .Lcopy_generic
	v_lshlrev_b32_e32 v3, 4, v2
	s_mov_b64 s[10:11], s[4:5]
	s_add_u32 s12, s16, 0x6198000
	s_addc_u32 s13, s17, 0
	global_load_dwordx4 v[100:103], v3, s[10:11]
	s_add_u32 s10, s10, 0x200000
	s_addc_u32 s11, s11, 0
	global_load_dwordx4 v[104:107], v3, s[10:11]
	s_add_u32 s10, s10, 0x200000
	s_addc_u32 s11, s11, 0
	global_load_dwordx4 v[108:111], v3, s[10:11]
	s_add_u32 s10, s10, 0x200000
	s_addc_u32 s11, s11, 0
	global_load_dwordx4 v[112:115], v3, s[10:11]
	s_add_u32 s10, s10, 0x200000
	s_addc_u32 s11, s11, 0
	global_load_dwordx4 v[116:119], v3, s[10:11]
	s_add_u32 s10, s10, 0x200000
	s_addc_u32 s11, s11, 0
	global_load_dwordx4 v[120:123], v3, s[10:11]
	s_add_u32 s10, s10, 0x200000
	s_addc_u32 s11, s11, 0
	global_load_dwordx4 v[124:127], v3, s[10:11]
	s_add_u32 s10, s10, 0x200000
	s_addc_u32 s11, s11, 0
	global_load_dwordx4 v[128:131], v3, s[10:11]
	s_waitcnt vmcnt(0)
	global_store_dwordx4 v3, v[100:103], s[12:13]
	s_add_u32 s12, s12, 0x200000
	s_addc_u32 s13, s13, 0
	global_store_dwordx4 v3, v[104:107], s[12:13]
	s_add_u32 s12, s12, 0x200000
	s_addc_u32 s13, s13, 0
	global_store_dwordx4 v3, v[108:111], s[12:13]
	s_add_u32 s12, s12, 0x200000
	s_addc_u32 s13, s13, 0
	global_store_dwordx4 v3, v[112:115], s[12:13]
	s_add_u32 s12, s12, 0x200000
	s_addc_u32 s13, s13, 0
	global_store_dwordx4 v3, v[116:119], s[12:13]
	s_add_u32 s12, s12, 0x200000
	s_addc_u32 s13, s13, 0
	global_store_dwordx4 v3, v[120:123], s[12:13]
	s_add_u32 s12, s12, 0x200000
	s_addc_u32 s13, s13, 0
	global_store_dwordx4 v3, v[124:127], s[12:13]
	s_add_u32 s12, s12, 0x200000
	s_addc_u32 s13, s13, 0
	global_store_dwordx4 v3, v[128:131], s[12:13]
	s_nop 1
	s_add_u32 s10, s6, 0x0
	s_addc_u32 s11, s7, 0
	s_add_u32 s12, s16, 0x7198000
	s_addc_u32 s13, s17, 0
	global_load_dwordx4 v[100:103], v3, s[10:11]
	s_add_u32 s10, s10, 0x200000
	s_addc_u32 s11, s11, 0
	global_load_dwordx4 v[104:107], v3, s[10:11]
	s_add_u32 s10, s10, 0x200000
	s_addc_u32 s11, s11, 0
	global_load_dwordx4 v[108:111], v3, s[10:11]
	s_add_u32 s10, s10, 0x200000
	s_addc_u32 s11, s11, 0
	global_load_dwordx4 v[112:115], v3, s[10:11]
	s_add_u32 s10, s10, 0x200000
	s_addc_u32 s11, s11, 0
	global_load_dwordx4 v[116:119], v3, s[10:11]
	s_add_u32 s10, s10, 0x200000
	s_addc_u32 s11, s11, 0
	global_load_dwordx4 v[120:123], v3, s[10:11]
	s_add_u32 s10, s10, 0x200000
	s_addc_u32 s11, s11, 0
	global_load_dwordx4 v[124:127], v3, s[10:11]
	s_add_u32 s10, s10, 0x200000
	s_addc_u32 s11, s11, 0
	global_load_dwordx4 v[128:131], v3, s[10:11]
	s_waitcnt vmcnt(0)
	global_store_dwordx4 v3, v[100:103], s[12:13]
	s_add_u32 s12, s12, 0x200000
	s_addc_u32 s13, s13, 0
	global_store_dwordx4 v3, v[104:107], s[12:13]
	s_add_u32 s12, s12, 0x200000
	s_addc_u32 s13, s13, 0
	global_store_dwordx4 v3, v[108:111], s[12:13]
	s_add_u32 s12, s12, 0x200000
	s_addc_u32 s13, s13, 0
	global_store_dwordx4 v3, v[112:115], s[12:13]
	s_add_u32 s12, s12, 0x200000
	s_addc_u32 s13, s13, 0
	global_store_dwordx4 v3, v[116:119], s[12:13]
	s_add_u32 s12, s12, 0x200000
	s_addc_u32 s13, s13, 0
	global_store_dwordx4 v3, v[120:123], s[12:13]
	s_add_u32 s12, s12, 0x200000
	s_addc_u32 s13, s13, 0
	global_store_dwordx4 v3, v[124:127], s[12:13]
	s_add_u32 s12, s12, 0x200000
	s_addc_u32 s13, s13, 0
	global_store_dwordx4 v3, v[128:131], s[12:13]
	s_nop 1
	s_add_u32 s10, s6, 0x1000000
	s_addc_u32 s11, s7, 0
	s_add_u32 s12, s16, 0x8198000
	s_addc_u32 s13, s17, 0
	global_load_dwordx4 v[100:103], v3, s[10:11]
	s_add_u32 s10, s10, 0x200000
	s_addc_u32 s11, s11, 0
	global_load_dwordx4 v[104:107], v3, s[10:11]
	s_add_u32 s10, s10, 0x200000
	s_addc_u32 s11, s11, 0
	global_load_dwordx4 v[108:111], v3, s[10:11]
	s_add_u32 s10, s10, 0x200000
	s_addc_u32 s11, s11, 0
	global_load_dwordx4 v[112:115], v3, s[10:11]
	s_add_u32 s10, s10, 0x200000
	s_addc_u32 s11, s11, 0
	global_load_dwordx4 v[116:119], v3, s[10:11]
	s_add_u32 s10, s10, 0x200000
	s_addc_u32 s11, s11, 0
	global_load_dwordx4 v[120:123], v3, s[10:11]
	s_add_u32 s10, s10, 0x200000
	s_addc_u32 s11, s11, 0
	global_load_dwordx4 v[124:127], v3, s[10:11]
	s_add_u32 s10, s10, 0x200000
	s_addc_u32 s11, s11, 0
	global_load_dwordx4 v[128:131], v3, s[10:11]
	s_waitcnt vmcnt(0)
	global_store_dwordx4 v3, v[100:103], s[12:13]
	s_add_u32 s12, s12, 0x200000
	s_addc_u32 s13, s13, 0
	global_store_dwordx4 v3, v[104:107], s[12:13]
	s_add_u32 s12, s12, 0x200000
	s_addc_u32 s13, s13, 0
	global_store_dwordx4 v3, v[108:111], s[12:13]
	s_add_u32 s12, s12, 0x200000
	s_addc_u32 s13, s13, 0
	global_store_dwordx4 v3, v[112:115], s[12:13]
	s_add_u32 s12, s12, 0x200000
	s_addc_u32 s13, s13, 0
	global_store_dwordx4 v3, v[116:119], s[12:13]
	s_add_u32 s12, s12, 0x200000
	s_addc_u32 s13, s13, 0
	global_store_dwordx4 v3, v[120:123], s[12:13]
	s_add_u32 s12, s12, 0x200000
	s_addc_u32 s13, s13, 0
	global_store_dwordx4 v3, v[124:127], s[12:13]
	s_add_u32 s12, s12, 0x200000
	s_addc_u32 s13, s13, 0
	global_store_dwordx4 v3, v[128:131], s[12:13]
	s_nop 1
	s_branch .LBB0_66
.Lcopy_generic:
	s_add_u32 s8, s16, 0x6198000
	s_addc_u32 s9, s17, 0
	s_mov_b64 s[10:11], 0
	s_mov_b32 s14, 0x100000
	s_lshl_b32 s15, s12, 8
	s_mov_b32 s12, 0xff000000
	v_mov_b32_e32 v1, 0
	s_mov_b32 s13, -1
	s_mov_b32 s18, 0x2fffff

.LBB0_603:
	global_load_dwordx4 v[100:103], v[4:5], off offset:-16
	global_load_dwordx4 v[104:107], v[4:5], off
	global_load_dwordx4 v[108:111], v[4:5], off offset:16
	global_load_dwordx4 v[112:115], v[4:5], off offset:32
	global_load_dwordx4 v[116:119], v[4:5], off offset:48
	global_load_dwordx4 v[120:123], v[4:5], off offset:64
	global_load_dwordx4 v[124:127], v[4:5], off offset:80
	global_load_dwordx4 v[128:131], v[4:5], off offset:96
	v_lshl_add_u64 v[164:165], v[2:3], 0, s[28:29]
	v_lshl_add_u64 v[166:167], v[164:165], 0, s[28:29]
	v_lshl_add_u64 v[168:169], v[166:167], 0, s[28:29]
	global_load_ushort v132, v[2:3], off offset:-2048
	global_load_ushort v133, v[2:3], off offset:-1536
	global_load_ushort v134, v[2:3], off offset:-1024
	global_load_ushort v135, v[2:3], off offset:-512
	global_load_ushort v136, v[2:3], off
	global_load_ushort v137, v[2:3], off offset:512
	global_load_ushort v138, v[2:3], off offset:1024
	global_load_ushort v139, v[2:3], off offset:1536
	global_load_ushort v140, v[164:165], off offset:-2048
	global_load_ushort v141, v[164:165], off offset:-1536
	global_load_ushort v142, v[164:165], off offset:-1024
	global_load_ushort v143, v[164:165], off offset:-512
	global_load_ushort v144, v[164:165], off
	global_load_ushort v145, v[164:165], off offset:512
	global_load_ushort v146, v[164:165], off offset:1024
	global_load_ushort v147, v[164:165], off offset:1536
	global_load_ushort v148, v[166:167], off offset:-2048
	global_load_ushort v149, v[166:167], off offset:-1536
	global_load_ushort v150, v[166:167], off offset:-1024
	global_load_ushort v151, v[166:167], off offset:-512
	global_load_ushort v152, v[166:167], off
	global_load_ushort v153, v[166:167], off offset:512
	global_load_ushort v154, v[166:167], off offset:1024
	global_load_ushort v155, v[166:167], off offset:1536
	global_load_ushort v156, v[168:169], off offset:-2048
	global_load_ushort v157, v[168:169], off offset:-1536
	global_load_ushort v158, v[168:169], off offset:-1024
	global_load_ushort v159, v[168:169], off offset:-512
	global_load_ushort v160, v[168:169], off
	global_load_ushort v161, v[168:169], off offset:512
	global_load_ushort v162, v[168:169], off offset:1024
	global_load_ushort v163, v[168:169], off offset:1536
	s_waitcnt vmcnt(0)
	v_lshlrev_b32_e32 v132, 16, v132
	v_fmac_f32_e32 v1, v100, v132
	v_lshlrev_b32_e32 v133, 16, v133
	v_fmac_f32_e32 v1, v101, v133
	v_lshlrev_b32_e32 v134, 16, v134
	v_fmac_f32_e32 v1, v102, v134
	v_lshlrev_b32_e32 v135, 16, v135
	v_fmac_f32_e32 v1, v103, v135
	v_lshlrev_b32_e32 v136, 16, v136
	v_fmac_f32_e32 v1, v104, v136
	v_lshlrev_b32_e32 v137, 16, v137
	v_fmac_f32_e32 v1, v105, v137
	v_lshlrev_b32_e32 v138, 16, v138
	v_fmac_f32_e32 v1, v106, v138
	v_lshlrev_b32_e32 v139, 16, v139
	v_fmac_f32_e32 v1, v107, v139
	v_lshlrev_b32_e32 v140, 16, v140
	v_fmac_f32_e32 v1, v108, v140
	v_lshlrev_b32_e32 v141, 16, v141
	v_fmac_f32_e32 v1, v109, v141
	v_lshlrev_b32_e32 v142, 16, v142
	v_fmac_f32_e32 v1, v110, v142
	v_lshlrev_b32_e32 v143, 16, v143
	v_fmac_f32_e32 v1, v111, v143
	v_lshlrev_b32_e32 v144, 16, v144
	v_fmac_f32_e32 v1, v112, v144
	v_lshlrev_b32_e32 v145, 16, v145
	v_fmac_f32_e32 v1, v113, v145
	v_lshlrev_b32_e32 v146, 16, v146
	v_fmac_f32_e32 v1, v114, v146
	v_lshlrev_b32_e32 v147, 16, v147
	v_fmac_f32_e32 v1, v115, v147
	v_lshlrev_b32_e32 v148, 16, v148
	v_fmac_f32_e32 v1, v116, v148
	v_lshlrev_b32_e32 v149, 16, v149
	v_fmac_f32_e32 v1, v117, v149
	v_lshlrev_b32_e32 v150, 16, v150
	v_fmac_f32_e32 v1, v118, v150
	v_lshlrev_b32_e32 v151, 16, v151
	v_fmac_f32_e32 v1, v119, v151
	v_lshlrev_b32_e32 v152, 16, v152
	v_fmac_f32_e32 v1, v120, v152
	v_lshlrev_b32_e32 v153, 16, v153
	v_fmac_f32_e32 v1, v121, v153
	v_lshlrev_b32_e32 v154, 16, v154
	v_fmac_f32_e32 v1, v122, v154
	v_lshlrev_b32_e32 v155, 16, v155
	v_fmac_f32_e32 v1, v123, v155
	v_lshlrev_b32_e32 v156, 16, v156
	v_fmac_f32_e32 v1, v124, v156
	v_lshlrev_b32_e32 v157, 16, v157
	v_fmac_f32_e32 v1, v125, v157
	v_lshlrev_b32_e32 v158, 16, v158
	v_fmac_f32_e32 v1, v126, v158
	v_lshlrev_b32_e32 v159, 16, v159
	v_fmac_f32_e32 v1, v127, v159
	v_lshlrev_b32_e32 v160, 16, v160
	v_fmac_f32_e32 v1, v128, v160
	v_lshlrev_b32_e32 v161, 16, v161
	v_fmac_f32_e32 v1, v129, v161
	v_lshlrev_b32_e32 v162, 16, v162
	v_fmac_f32_e32 v1, v130, v162
	v_lshlrev_b32_e32 v163, 16, v163
	v_fmac_f32_e32 v1, v131, v163
	s_add_i32 s2, s2, 1
	v_lshl_add_u64 v[2:3], v[2:3], 0, s[40:41]
	s_cmp_eq_u32 s2, 4
	v_lshl_add_u64 v[4:5], v[4:5], 0, s[94:95]
	s_cbranch_scc0 .LBB0_603
	s_movk_i32 s2, 0x80
	v_lshlrev_b32_e32 v2, 2, v64
	v_cmp_gt_i32_e32 vcc, s2, v64
	s_barrier
	ds_write_b32 v2, v1
	s_waitcnt lgkmcnt(0)
	s_barrier
	s_and_saveexec_b64 s[4:5], vcc
	s_cbranch_execz .LBB0_608
	s_lshl_b64 s[10:11], s[10:11], 10
	ds_read2st64_b32 v[2:3], v2 offset1:2
	s_add_u32 s10, s8, s10
	s_addc_u32 s11, s9, s11
	v_lshlrev_b32_e32 v0, 2, v0
	v_mov_b32_e32 v1, v96
	v_lshl_add_u64 v[0:1], s[10:11], 0, v[0:1]
	v_add_co_u32_e32 v0, vcc, 0x13000000, v0
	s_waitcnt lgkmcnt(0)
	v_add_f32_e32 v2, v2, v3
	v_addc_co_u32_e32 v1, vcc, 0, v1, vcc
	global_store_dword v[0:1], v2, off
